# lever9 variant: MFMA handoff path of both GEMM K-loops trimmed - every s_setprio flip and the redundant post-barrier lgkmcnt(0) deleted (load segments carry no VALU since the saddr change)
# speedup vs baseline: 1.0059x; 1.0059x over previous
.Lpl_out_j1:
	s_waitcnt lgkmcnt(0)
	s_barrier
	v_mfma_f32_16x16x32_bf16 v[134:137], v[0:3], v[188:191], 0
	v_mfma_f32_16x16x32_bf16 v[130:133], v[138:141], v[188:191], 0
	v_mfma_f32_16x16x32_bf16 v[118:121], v[0:3], v[196:199], 0
	v_mfma_f32_16x16x32_bf16 v[114:117], v[138:141], v[196:199], 0
	v_mfma_f32_16x16x32_bf16 v[102:105], v[0:3], v[204:207], 0
	v_mfma_f32_16x16x32_bf16 v[98:101], v[138:141], v[204:207], 0
	v_mfma_f32_16x16x32_bf16 v[84:87], v[0:3], v[238:241], 0
	v_mfma_f32_16x16x32_bf16 v[80:83], v[138:141], v[238:241], 0
	v_mfma_f32_16x16x32_bf16 v[134:137], v[4:7], v[192:195], v[134:137]
	v_mfma_f32_16x16x32_bf16 v[130:133], v[142:145], v[192:195], v[130:133]
	v_mfma_f32_16x16x32_bf16 v[118:121], v[4:7], v[200:203], v[118:121]
	v_mfma_f32_16x16x32_bf16 v[114:117], v[142:145], v[200:203], v[114:117]
	v_mfma_f32_16x16x32_bf16 v[102:105], v[4:7], v[234:237], v[102:105]
	v_mfma_f32_16x16x32_bf16 v[98:101], v[142:145], v[234:237], v[98:101]
	v_mfma_f32_16x16x32_bf16 v[84:87], v[4:7], v[242:245], v[84:87]
	v_mfma_f32_16x16x32_bf16 v[80:83], v[142:145], v[242:245], v[80:83]
	v_mfma_f32_16x16x32_bf16 v[126:129], v[146:149], v[188:191], 0
	v_mfma_f32_16x16x32_bf16 v[122:125], v[180:183], v[188:191], 0
	v_mfma_f32_16x16x32_bf16 v[110:113], v[146:149], v[196:199], 0
	v_mfma_f32_16x16x32_bf16 v[106:109], v[180:183], v[196:199], 0
	v_mfma_f32_16x16x32_bf16 v[92:95], v[146:149], v[204:207], 0
	v_mfma_f32_16x16x32_bf16 v[88:91], v[180:183], v[204:207], 0
	v_mfma_f32_16x16x32_bf16 v[76:79], v[146:149], v[238:241], 0
	v_mfma_f32_16x16x32_bf16 v[72:75], v[180:183], v[238:241], 0
	v_mfma_f32_16x16x32_bf16 v[126:129], v[150:153], v[192:195], v[126:129]
	v_mfma_f32_16x16x32_bf16 v[122:125], v[184:187], v[192:195], v[122:125]
	v_mfma_f32_16x16x32_bf16 v[110:113], v[150:153], v[200:203], v[110:113]
	v_mfma_f32_16x16x32_bf16 v[106:109], v[184:187], v[200:203], v[106:109]
	v_mfma_f32_16x16x32_bf16 v[92:95], v[150:153], v[234:237], v[92:95]
	v_mfma_f32_16x16x32_bf16 v[88:91], v[184:187], v[234:237], v[88:91]
	v_mfma_f32_16x16x32_bf16 v[76:79], v[150:153], v[242:245], v[76:79]
	v_mfma_f32_16x16x32_bf16 v[72:75], v[184:187], v[242:245], v[72:75]
	s_barrier
	s_add_i32 s23, s23, s58
	s_mov_b32 m0, s23
	ds_read_b128 v[188:191], v231 offset:16384
	ds_read_b128 v[192:195], v231 offset:17408
	ds_read_b128 v[196:199], v231 offset:18432
	ds_read_b128 v[200:203], v231 offset:19456
	ds_read_b128 v[204:207], v231 offset:20480
	ds_read_b128 v[234:237], v231 offset:21504
	ds_read_b128 v[238:241], v231 offset:22528
	ds_read_b128 v[242:245], v231 offset:23552
	global_load_lds_dwordx4 v156, s[12:13]
	s_add_i32 m0, s23, 0x2000
	s_add_u32 s26, s12, 0x10000
	s_addc_u32 s27, s13, 0
	s_add_i32 s23, s31, s58
	global_load_lds_dwordx4 v160, s[12:13]
	s_mov_b32 m0, s23
	s_nop 0
	global_load_lds_dwordx4 v156, s[26:27]
	s_add_i32 m0, s23, 0x2000
	s_nop 0
	global_load_lds_dwordx4 v160, s[26:27]
	s_mov_b64 s[26:27], s[14:15]
	s_mov_b32 m0, s69
	s_nop 0
	global_load_lds_dwordx4 v154, s[14:15]
	s_mov_b32 m0, s70
	s_nop 0
	global_load_lds_dwordx4 v158, s[14:15]
	s_cmp_lg_u32 s100, 0
	s_cbranch_scc1 .Lpl_out_r2
	s_waitcnt vmcnt(8)
	s_branch .Lpl_out_j2

.Lpl_out_j2:
	s_mov_b32 s100, 0
	s_waitcnt lgkmcnt(0)
	s_barrier
	v_mfma_f32_16x16x32_bf16 v[68:71], v[0:3], v[188:191], 0
	v_mfma_f32_16x16x32_bf16 v[64:67], v[138:141], v[188:191], 0
	v_mfma_f32_16x16x32_bf16 v[52:55], v[0:3], v[196:199], 0
	v_mfma_f32_16x16x32_bf16 v[48:51], v[138:141], v[196:199], 0
	v_mfma_f32_16x16x32_bf16 v[36:39], v[0:3], v[204:207], 0
	v_mfma_f32_16x16x32_bf16 v[32:35], v[138:141], v[204:207], 0
	v_mfma_f32_16x16x32_bf16 v[0:3], v[0:3], v[238:241], 0
	v_mfma_f32_16x16x32_bf16 v[68:71], v[4:7], v[192:195], v[68:71]
	v_mfma_f32_16x16x32_bf16 v[64:67], v[142:145], v[192:195], v[64:67]
	v_mfma_f32_16x16x32_bf16 v[52:55], v[4:7], v[200:203], v[52:55]
	v_mfma_f32_16x16x32_bf16 v[48:51], v[142:145], v[200:203], v[48:51]
	v_mfma_f32_16x16x32_bf16 v[36:39], v[4:7], v[234:237], v[36:39]
	v_mfma_f32_16x16x32_bf16 v[32:35], v[142:145], v[234:237], v[32:35]
	v_mfma_f32_16x16x32_bf16 v[0:3], v[4:7], v[242:245], v[0:3]
	v_mfma_f32_16x16x32_bf16 v[4:7], v[138:141], v[238:241], 0
	v_mfma_f32_16x16x32_bf16 v[4:7], v[142:145], v[242:245], v[4:7]
	v_mfma_f32_16x16x32_bf16 v[16:19], v[146:149], v[188:191], 0
	v_mfma_f32_16x16x32_bf16 v[60:63], v[150:153], v[192:195], v[16:19]
	v_mfma_f32_16x16x32_bf16 v[16:19], v[180:183], v[188:191], 0
	v_mfma_f32_16x16x32_bf16 v[56:59], v[184:187], v[192:195], v[16:19]
	v_mfma_f32_16x16x32_bf16 v[16:19], v[146:149], v[196:199], 0
	v_mfma_f32_16x16x32_bf16 v[44:47], v[150:153], v[200:203], v[16:19]
	v_mfma_f32_16x16x32_bf16 v[16:19], v[180:183], v[196:199], 0
	v_mfma_f32_16x16x32_bf16 v[40:43], v[184:187], v[200:203], v[16:19]
	v_mfma_f32_16x16x32_bf16 v[16:19], v[146:149], v[204:207], 0
	v_mfma_f32_16x16x32_bf16 v[28:31], v[150:153], v[234:237], v[16:19]
	v_mfma_f32_16x16x32_bf16 v[16:19], v[180:183], v[204:207], 0
	v_mfma_f32_16x16x32_bf16 v[12:15], v[146:149], v[238:241], 0
	v_mfma_f32_16x16x32_bf16 v[8:11], v[180:183], v[238:241], 0
	v_mfma_f32_16x16x32_bf16 v[24:27], v[184:187], v[234:237], v[16:19]
	v_mfma_f32_16x16x32_bf16 v[12:15], v[150:153], v[242:245], v[12:15]
	v_mfma_f32_16x16x32_bf16 v[8:11], v[184:187], v[242:245], v[8:11]
	s_barrier
	s_add_i32 s23, 0, 0x1c000
	ds_read_b128 v[16:19], v253 offset:32768
	ds_read_b128 v[20:23], v253 offset:33792
	ds_read_b128 v[138:141], v253 offset:34816
	ds_read_b128 v[142:145], v253 offset:35840
	ds_read_b128 v[146:149], v253 offset:49152
	ds_read_b128 v[150:153], v253 offset:50176
	ds_read_b128 v[180:183], v253 offset:51200
	ds_read_b128 v[184:187], v253 offset:52224
	s_add_u32 s14, s14, 0x40000
	s_addc_u32 s15, s15, 0
	s_mov_b32 m0, s71
	ds_read_b128 v[188:191], v231 offset:32768
	ds_read_b128 v[192:195], v231 offset:33792
	ds_read_b128 v[196:199], v231 offset:34816
	ds_read_b128 v[200:203], v231 offset:35840
	ds_read_b128 v[204:207], v231 offset:36864
	ds_read_b128 v[234:237], v231 offset:37888
	ds_read_b128 v[238:241], v231 offset:38912
	ds_read_b128 v[242:245], v231 offset:39936
	global_load_lds_dwordx4 v154, s[14:15]
	s_mov_b32 m0, s76
	s_nop 0
	global_load_lds_dwordx4 v158, s[14:15]
	s_waitcnt vmcnt(8)
	s_waitcnt lgkmcnt(0)
	s_barrier
	v_mfma_f32_16x16x32_bf16 v[134:137], v[16:19], v[188:191], v[134:137]
	v_mfma_f32_16x16x32_bf16 v[130:133], v[138:141], v[188:191], v[130:133]
	v_mfma_f32_16x16x32_bf16 v[118:121], v[16:19], v[196:199], v[118:121]
	v_mfma_f32_16x16x32_bf16 v[114:117], v[138:141], v[196:199], v[114:117]
	v_mfma_f32_16x16x32_bf16 v[102:105], v[16:19], v[204:207], v[102:105]
	v_mfma_f32_16x16x32_bf16 v[98:101], v[138:141], v[204:207], v[98:101]
	v_mfma_f32_16x16x32_bf16 v[84:87], v[16:19], v[238:241], v[84:87]
	v_mfma_f32_16x16x32_bf16 v[80:83], v[138:141], v[238:241], v[80:83]
	v_mfma_f32_16x16x32_bf16 v[134:137], v[20:23], v[192:195], v[134:137]
	v_mfma_f32_16x16x32_bf16 v[130:133], v[142:145], v[192:195], v[130:133]
	v_mfma_f32_16x16x32_bf16 v[118:121], v[20:23], v[200:203], v[118:121]
	v_mfma_f32_16x16x32_bf16 v[114:117], v[142:145], v[200:203], v[114:117]
	v_mfma_f32_16x16x32_bf16 v[102:105], v[20:23], v[234:237], v[102:105]
	v_mfma_f32_16x16x32_bf16 v[98:101], v[142:145], v[234:237], v[98:101]
	v_mfma_f32_16x16x32_bf16 v[84:87], v[20:23], v[242:245], v[84:87]
	v_mfma_f32_16x16x32_bf16 v[80:83], v[142:145], v[242:245], v[80:83]
	v_mfma_f32_16x16x32_bf16 v[126:129], v[146:149], v[188:191], v[126:129]
	v_mfma_f32_16x16x32_bf16 v[122:125], v[180:183], v[188:191], v[122:125]
	v_mfma_f32_16x16x32_bf16 v[110:113], v[146:149], v[196:199], v[110:113]
	v_mfma_f32_16x16x32_bf16 v[106:109], v[180:183], v[196:199], v[106:109]
	v_mfma_f32_16x16x32_bf16 v[92:95], v[146:149], v[204:207], v[92:95]
	v_mfma_f32_16x16x32_bf16 v[88:91], v[180:183], v[204:207], v[88:91]
	v_mfma_f32_16x16x32_bf16 v[76:79], v[146:149], v[238:241], v[76:79]
	v_mfma_f32_16x16x32_bf16 v[72:75], v[180:183], v[238:241], v[72:75]
	v_mfma_f32_16x16x32_bf16 v[126:129], v[150:153], v[192:195], v[126:129]
	v_mfma_f32_16x16x32_bf16 v[122:125], v[184:187], v[192:195], v[122:125]
	v_mfma_f32_16x16x32_bf16 v[110:113], v[150:153], v[200:203], v[110:113]
	v_mfma_f32_16x16x32_bf16 v[106:109], v[184:187], v[200:203], v[106:109]
	v_mfma_f32_16x16x32_bf16 v[92:95], v[150:153], v[234:237], v[92:95]
	v_mfma_f32_16x16x32_bf16 v[88:91], v[184:187], v[234:237], v[88:91]
	v_mfma_f32_16x16x32_bf16 v[76:79], v[150:153], v[242:245], v[76:79]
	v_mfma_f32_16x16x32_bf16 v[72:75], v[184:187], v[242:245], v[72:75]
	s_barrier
	s_add_i32 s14, s67, s58
	s_add_i32 m0, s14, 0xffffff80
	ds_read_b128 v[188:191], v231 offset:49152
	ds_read_b128 v[192:195], v231 offset:50176
	ds_read_b128 v[196:199], v231 offset:51200
	ds_read_b128 v[200:203], v231 offset:52224
	ds_read_b128 v[204:207], v231 offset:53248
	ds_read_b128 v[234:237], v231 offset:54272
	ds_read_b128 v[238:241], v231 offset:55296
	ds_read_b128 v[242:245], v231 offset:56320
	global_load_lds_dwordx4 v156, s[12:13] offset:128
	s_add_i32 m0, s14, 0x1f80
	s_add_i32 s14, s23, s58
	global_load_lds_dwordx4 v160, s[12:13] offset:128
	s_add_u32 s12, s12, 0x10080
	s_addc_u32 s13, s13, 0
	s_mov_b32 m0, s14
	s_nop 0
	global_load_lds_dwordx4 v156, s[12:13]
	s_add_i32 m0, s14, 0x2000
	s_nop 0
	global_load_lds_dwordx4 v160, s[12:13]
	s_add_i32 m0, s96, 0xffffff80
	s_nop 0
	global_load_lds_dwordx4 v154, s[26:27] offset:128
	s_add_i32 m0, s36, 0xffffff80
	s_nop 0
	global_load_lds_dwordx4 v158, s[26:27] offset:128
	s_waitcnt vmcnt(8)
	s_waitcnt lgkmcnt(0)
	s_barrier
	v_mfma_f32_16x16x32_bf16 v[68:71], v[16:19], v[188:191], v[68:71]
	v_mfma_f32_16x16x32_bf16 v[52:55], v[16:19], v[196:199], v[52:55]
	v_mfma_f32_16x16x32_bf16 v[36:39], v[16:19], v[204:207], v[36:39]
	v_mfma_f32_16x16x32_bf16 v[0:3], v[16:19], v[238:241], v[0:3]
	v_mfma_f32_16x16x32_bf16 v[68:71], v[20:23], v[192:195], v[68:71]
	v_mfma_f32_16x16x32_bf16 v[64:67], v[138:141], v[188:191], v[64:67]
	v_mfma_f32_16x16x32_bf16 v[52:55], v[20:23], v[200:203], v[52:55]
	v_mfma_f32_16x16x32_bf16 v[48:51], v[138:141], v[196:199], v[48:51]
	v_mfma_f32_16x16x32_bf16 v[36:39], v[20:23], v[234:237], v[36:39]
	v_mfma_f32_16x16x32_bf16 v[32:35], v[138:141], v[204:207], v[32:35]
	v_mfma_f32_16x16x32_bf16 v[20:23], v[20:23], v[242:245], v[0:3]
	v_mfma_f32_16x16x32_bf16 v[0:3], v[138:141], v[238:241], v[4:7]
	v_mfma_f32_16x16x32_bf16 v[64:67], v[142:145], v[192:195], v[64:67]
	v_mfma_f32_16x16x32_bf16 v[48:51], v[142:145], v[200:203], v[48:51]
	v_mfma_f32_16x16x32_bf16 v[32:35], v[142:145], v[234:237], v[32:35]
	v_mfma_f32_16x16x32_bf16 v[16:19], v[142:145], v[242:245], v[0:3]
	v_mfma_f32_16x16x32_bf16 v[0:3], v[146:149], v[188:191], v[60:63]
	v_mfma_f32_16x16x32_bf16 v[60:63], v[150:153], v[192:195], v[0:3]
	v_mfma_f32_16x16x32_bf16 v[0:3], v[180:183], v[188:191], v[56:59]
	v_mfma_f32_16x16x32_bf16 v[56:59], v[184:187], v[192:195], v[0:3]
	v_mfma_f32_16x16x32_bf16 v[0:3], v[146:149], v[196:199], v[44:47]
	v_mfma_f32_16x16x32_bf16 v[44:47], v[150:153], v[200:203], v[0:3]
	v_mfma_f32_16x16x32_bf16 v[0:3], v[180:183], v[196:199], v[40:43]
	v_mfma_f32_16x16x32_bf16 v[40:43], v[184:187], v[200:203], v[0:3]
	v_mfma_f32_16x16x32_bf16 v[0:3], v[146:149], v[204:207], v[28:31]
	v_mfma_f32_16x16x32_bf16 v[28:31], v[150:153], v[234:237], v[0:3]
	v_mfma_f32_16x16x32_bf16 v[0:3], v[180:183], v[204:207], v[24:27]
	v_mfma_f32_16x16x32_bf16 v[24:27], v[184:187], v[234:237], v[0:3]
	v_mfma_f32_16x16x32_bf16 v[0:3], v[146:149], v[238:241], v[12:15]
	v_mfma_f32_16x16x32_bf16 v[12:15], v[150:153], v[242:245], v[0:3]
	v_mfma_f32_16x16x32_bf16 v[0:3], v[180:183], v[238:241], v[8:11]
	v_mfma_f32_16x16x32_bf16 v[8:11], v[184:187], v[242:245], v[0:3]
	s_barrier
	s_add_i32 s22, s22, 2
	s_add_u32 s2, s2, 0x100
	s_addc_u32 s3, s3, 0
	s_add_u32 s20, s20, 0x100
	s_addc_u32 s21, s21, 0
	.p2align 6
.LBB0_405:
	s_add_u32 s12, s2, 0xfffc0080
	s_addc_u32 s13, s3, -1
	s_add_i32 s23, 0, 0x10000
	s_cmp_eq_u32 s22, 12
	s_cselect_b32 s15, s16, s13
	s_cselect_b32 s14, s17, s12
	s_cselect_b32 s13, s18, s21
	s_cselect_b32 s12, s19, s20
	s_add_i32 s31, 0, 0x14000
	ds_read_b128 v[0:3], v253
	ds_read_b128 v[4:7], v253 offset:1024
	ds_read_b128 v[138:141], v253 offset:2048
	ds_read_b128 v[142:145], v253 offset:3072
	ds_read_b128 v[146:149], v253 offset:16384
	ds_read_b128 v[150:153], v253 offset:17408
	ds_read_b128 v[180:183], v253 offset:18432
	ds_read_b128 v[184:187], v253 offset:19456
	s_add_i32 m0, s69, 0xc000
	ds_read_b128 v[188:191], v231
	ds_read_b128 v[192:195], v231 offset:1024
	ds_read_b128 v[196:199], v231 offset:2048
	ds_read_b128 v[200:203], v231 offset:3072
	ds_read_b128 v[204:207], v231 offset:4096
	ds_read_b128 v[234:237], v231 offset:5120
	ds_read_b128 v[238:241], v231 offset:6144
	ds_read_b128 v[242:245], v231 offset:7168
	global_load_lds_dwordx4 v166, s[2:3]
	s_add_i32 m0, s69, 0xe000
	s_nop 0
	global_load_lds_dwordx4 v168, s[2:3]
	s_waitcnt vmcnt(8)
	s_waitcnt lgkmcnt(0)
	s_barrier
	v_mfma_f32_16x16x32_bf16 v[134:137], v[0:3], v[188:191], v[134:137]
	v_mfma_f32_16x16x32_bf16 v[130:133], v[138:141], v[188:191], v[130:133]
	v_mfma_f32_16x16x32_bf16 v[118:121], v[0:3], v[196:199], v[118:121]
	v_mfma_f32_16x16x32_bf16 v[114:117], v[138:141], v[196:199], v[114:117]
	v_mfma_f32_16x16x32_bf16 v[102:105], v[0:3], v[204:207], v[102:105]
	v_mfma_f32_16x16x32_bf16 v[98:101], v[138:141], v[204:207], v[98:101]
	v_mfma_f32_16x16x32_bf16 v[84:87], v[0:3], v[238:241], v[84:87]
	v_mfma_f32_16x16x32_bf16 v[80:83], v[138:141], v[238:241], v[80:83]
	v_mfma_f32_16x16x32_bf16 v[134:137], v[4:7], v[192:195], v[134:137]
	v_mfma_f32_16x16x32_bf16 v[130:133], v[142:145], v[192:195], v[130:133]
	v_mfma_f32_16x16x32_bf16 v[118:121], v[4:7], v[200:203], v[118:121]
	v_mfma_f32_16x16x32_bf16 v[114:117], v[142:145], v[200:203], v[114:117]
	v_mfma_f32_16x16x32_bf16 v[102:105], v[4:7], v[234:237], v[102:105]
	v_mfma_f32_16x16x32_bf16 v[98:101], v[142:145], v[234:237], v[98:101]
	v_mfma_f32_16x16x32_bf16 v[84:87], v[4:7], v[242:245], v[84:87]
	v_mfma_f32_16x16x32_bf16 v[80:83], v[142:145], v[242:245], v[80:83]
	v_mfma_f32_16x16x32_bf16 v[126:129], v[146:149], v[188:191], v[126:129]
	v_mfma_f32_16x16x32_bf16 v[122:125], v[180:183], v[188:191], v[122:125]
	v_mfma_f32_16x16x32_bf16 v[110:113], v[146:149], v[196:199], v[110:113]
	v_mfma_f32_16x16x32_bf16 v[106:109], v[180:183], v[196:199], v[106:109]
	v_mfma_f32_16x16x32_bf16 v[92:95], v[146:149], v[204:207], v[92:95]
	v_mfma_f32_16x16x32_bf16 v[88:91], v[180:183], v[204:207], v[88:91]
	v_mfma_f32_16x16x32_bf16 v[76:79], v[146:149], v[238:241], v[76:79]
	v_mfma_f32_16x16x32_bf16 v[72:75], v[180:183], v[238:241], v[72:75]
	v_mfma_f32_16x16x32_bf16 v[126:129], v[150:153], v[192:195], v[126:129]
	v_mfma_f32_16x16x32_bf16 v[122:125], v[184:187], v[192:195], v[122:125]
	v_mfma_f32_16x16x32_bf16 v[110:113], v[150:153], v[200:203], v[110:113]
	v_mfma_f32_16x16x32_bf16 v[106:109], v[184:187], v[200:203], v[106:109]
	v_mfma_f32_16x16x32_bf16 v[92:95], v[150:153], v[234:237], v[92:95]
	v_mfma_f32_16x16x32_bf16 v[88:91], v[184:187], v[234:237], v[88:91]
	v_mfma_f32_16x16x32_bf16 v[76:79], v[150:153], v[242:245], v[76:79]
	v_mfma_f32_16x16x32_bf16 v[72:75], v[184:187], v[242:245], v[72:75]
	s_barrier
	s_add_i32 s23, s23, s58
	s_mov_b32 m0, s23
	ds_read_b128 v[188:191], v231 offset:16384
	ds_read_b128 v[192:195], v231 offset:17408
	ds_read_b128 v[196:199], v231 offset:18432
	ds_read_b128 v[200:203], v231 offset:19456
	ds_read_b128 v[204:207], v231 offset:20480
	ds_read_b128 v[234:237], v231 offset:21504
	ds_read_b128 v[238:241], v231 offset:22528
	ds_read_b128 v[242:245], v231 offset:23552
	global_load_lds_dwordx4 v156, s[12:13]
	s_add_i32 m0, s23, 0x2000
	s_add_u32 s26, s12, 0x10000
	s_addc_u32 s27, s13, 0
	s_add_i32 s23, s31, s58
	global_load_lds_dwordx4 v160, s[12:13]
	s_mov_b32 m0, s23
	s_nop 0
	global_load_lds_dwordx4 v156, s[26:27]
	s_add_i32 m0, s23, 0x2000
	s_nop 0
	global_load_lds_dwordx4 v160, s[26:27]
	s_mov_b64 s[26:27], s[14:15]
	s_mov_b32 m0, s69
	s_nop 0
	global_load_lds_dwordx4 v154, s[14:15]
	s_mov_b32 m0, s70
	s_nop 0
	global_load_lds_dwordx4 v158, s[14:15]
	s_waitcnt vmcnt(8)
	s_waitcnt lgkmcnt(0)
	s_barrier
	v_mfma_f32_16x16x32_bf16 v[68:71], v[0:3], v[188:191], v[68:71]
	v_mfma_f32_16x16x32_bf16 v[64:67], v[138:141], v[188:191], v[64:67]
	v_mfma_f32_16x16x32_bf16 v[52:55], v[0:3], v[196:199], v[52:55]
	v_mfma_f32_16x16x32_bf16 v[48:51], v[138:141], v[196:199], v[48:51]
	v_mfma_f32_16x16x32_bf16 v[36:39], v[0:3], v[204:207], v[36:39]
	v_mfma_f32_16x16x32_bf16 v[32:35], v[138:141], v[204:207], v[32:35]
	v_mfma_f32_16x16x32_bf16 v[0:3], v[0:3], v[238:241], v[20:23]
	v_mfma_f32_16x16x32_bf16 v[68:71], v[4:7], v[192:195], v[68:71]
	v_mfma_f32_16x16x32_bf16 v[64:67], v[142:145], v[192:195], v[64:67]
	v_mfma_f32_16x16x32_bf16 v[52:55], v[4:7], v[200:203], v[52:55]
	v_mfma_f32_16x16x32_bf16 v[48:51], v[142:145], v[200:203], v[48:51]
	v_mfma_f32_16x16x32_bf16 v[36:39], v[4:7], v[234:237], v[36:39]
	v_mfma_f32_16x16x32_bf16 v[32:35], v[142:145], v[234:237], v[32:35]
	v_mfma_f32_16x16x32_bf16 v[0:3], v[4:7], v[242:245], v[0:3]
	v_mfma_f32_16x16x32_bf16 v[4:7], v[138:141], v[238:241], v[16:19]
	v_mfma_f32_16x16x32_bf16 v[4:7], v[142:145], v[242:245], v[4:7]
	v_mfma_f32_16x16x32_bf16 v[16:19], v[146:149], v[188:191], v[60:63]
	v_mfma_f32_16x16x32_bf16 v[60:63], v[150:153], v[192:195], v[16:19]
	v_mfma_f32_16x16x32_bf16 v[16:19], v[180:183], v[188:191], v[56:59]
	v_mfma_f32_16x16x32_bf16 v[56:59], v[184:187], v[192:195], v[16:19]
	v_mfma_f32_16x16x32_bf16 v[16:19], v[146:149], v[196:199], v[44:47]
	v_mfma_f32_16x16x32_bf16 v[44:47], v[150:153], v[200:203], v[16:19]
	v_mfma_f32_16x16x32_bf16 v[16:19], v[180:183], v[196:199], v[40:43]
	v_mfma_f32_16x16x32_bf16 v[40:43], v[184:187], v[200:203], v[16:19]
	v_mfma_f32_16x16x32_bf16 v[16:19], v[146:149], v[204:207], v[28:31]
	v_mfma_f32_16x16x32_bf16 v[28:31], v[150:153], v[234:237], v[16:19]
	v_mfma_f32_16x16x32_bf16 v[16:19], v[180:183], v[204:207], v[24:27]
	v_mfma_f32_16x16x32_bf16 v[12:15], v[146:149], v[238:241], v[12:15]
	v_mfma_f32_16x16x32_bf16 v[8:11], v[180:183], v[238:241], v[8:11]
	v_mfma_f32_16x16x32_bf16 v[24:27], v[184:187], v[234:237], v[16:19]
	v_mfma_f32_16x16x32_bf16 v[12:15], v[150:153], v[242:245], v[12:15]
	v_mfma_f32_16x16x32_bf16 v[8:11], v[184:187], v[242:245], v[8:11]
	s_barrier
	s_add_i32 s23, 0, 0x1c000
	ds_read_b128 v[16:19], v253 offset:32768
	ds_read_b128 v[20:23], v253 offset:33792
	ds_read_b128 v[138:141], v253 offset:34816
	ds_read_b128 v[142:145], v253 offset:35840
	ds_read_b128 v[146:149], v253 offset:49152
	ds_read_b128 v[150:153], v253 offset:50176
	ds_read_b128 v[180:183], v253 offset:51200
	ds_read_b128 v[184:187], v253 offset:52224
	s_add_u32 s14, s14, 0x40000
	s_addc_u32 s15, s15, 0
	s_mov_b32 m0, s71
	ds_read_b128 v[188:191], v231 offset:32768
	ds_read_b128 v[192:195], v231 offset:33792
	ds_read_b128 v[196:199], v231 offset:34816
	ds_read_b128 v[200:203], v231 offset:35840
	ds_read_b128 v[204:207], v231 offset:36864
	ds_read_b128 v[234:237], v231 offset:37888
	ds_read_b128 v[238:241], v231 offset:38912
	ds_read_b128 v[242:245], v231 offset:39936
	global_load_lds_dwordx4 v154, s[14:15]
	s_mov_b32 m0, s76
	s_nop 0
	global_load_lds_dwordx4 v158, s[14:15]
	s_waitcnt vmcnt(8)
	s_waitcnt lgkmcnt(0)
	s_barrier
	v_mfma_f32_16x16x32_bf16 v[134:137], v[16:19], v[188:191], v[134:137]
	v_mfma_f32_16x16x32_bf16 v[130:133], v[138:141], v[188:191], v[130:133]
	v_mfma_f32_16x16x32_bf16 v[118:121], v[16:19], v[196:199], v[118:121]
	v_mfma_f32_16x16x32_bf16 v[114:117], v[138:141], v[196:199], v[114:117]
	v_mfma_f32_16x16x32_bf16 v[102:105], v[16:19], v[204:207], v[102:105]
	v_mfma_f32_16x16x32_bf16 v[98:101], v[138:141], v[204:207], v[98:101]
	v_mfma_f32_16x16x32_bf16 v[84:87], v[16:19], v[238:241], v[84:87]
	v_mfma_f32_16x16x32_bf16 v[80:83], v[138:141], v[238:241], v[80:83]
	v_mfma_f32_16x16x32_bf16 v[134:137], v[20:23], v[192:195], v[134:137]
	v_mfma_f32_16x16x32_bf16 v[130:133], v[142:145], v[192:195], v[130:133]
	v_mfma_f32_16x16x32_bf16 v[118:121], v[20:23], v[200:203], v[118:121]
	v_mfma_f32_16x16x32_bf16 v[114:117], v[142:145], v[200:203], v[114:117]
	v_mfma_f32_16x16x32_bf16 v[102:105], v[20:23], v[234:237], v[102:105]
	v_mfma_f32_16x16x32_bf16 v[98:101], v[142:145], v[234:237], v[98:101]
	v_mfma_f32_16x16x32_bf16 v[84:87], v[20:23], v[242:245], v[84:87]
	v_mfma_f32_16x16x32_bf16 v[80:83], v[142:145], v[242:245], v[80:83]
	v_mfma_f32_16x16x32_bf16 v[126:129], v[146:149], v[188:191], v[126:129]
	v_mfma_f32_16x16x32_bf16 v[122:125], v[180:183], v[188:191], v[122:125]
	v_mfma_f32_16x16x32_bf16 v[110:113], v[146:149], v[196:199], v[110:113]
	v_mfma_f32_16x16x32_bf16 v[106:109], v[180:183], v[196:199], v[106:109]
	v_mfma_f32_16x16x32_bf16 v[92:95], v[146:149], v[204:207], v[92:95]
	v_mfma_f32_16x16x32_bf16 v[88:91], v[180:183], v[204:207], v[88:91]
	v_mfma_f32_16x16x32_bf16 v[76:79], v[146:149], v[238:241], v[76:79]
	v_mfma_f32_16x16x32_bf16 v[72:75], v[180:183], v[238:241], v[72:75]
	v_mfma_f32_16x16x32_bf16 v[126:129], v[150:153], v[192:195], v[126:129]
	v_mfma_f32_16x16x32_bf16 v[122:125], v[184:187], v[192:195], v[122:125]
	v_mfma_f32_16x16x32_bf16 v[110:113], v[150:153], v[200:203], v[110:113]
	v_mfma_f32_16x16x32_bf16 v[106:109], v[184:187], v[200:203], v[106:109]
	v_mfma_f32_16x16x32_bf16 v[92:95], v[150:153], v[234:237], v[92:95]
	v_mfma_f32_16x16x32_bf16 v[88:91], v[184:187], v[234:237], v[88:91]
	v_mfma_f32_16x16x32_bf16 v[76:79], v[150:153], v[242:245], v[76:79]
	v_mfma_f32_16x16x32_bf16 v[72:75], v[184:187], v[242:245], v[72:75]
	s_barrier
	s_add_i32 s14, s67, s58
	s_add_i32 m0, s14, 0xffffff80
	ds_read_b128 v[188:191], v231 offset:49152
	ds_read_b128 v[192:195], v231 offset:50176
	ds_read_b128 v[196:199], v231 offset:51200
	ds_read_b128 v[200:203], v231 offset:52224
	ds_read_b128 v[204:207], v231 offset:53248
	ds_read_b128 v[234:237], v231 offset:54272
	ds_read_b128 v[238:241], v231 offset:55296
	ds_read_b128 v[242:245], v231 offset:56320
	global_load_lds_dwordx4 v156, s[12:13] offset:128
	s_add_i32 m0, s14, 0x1f80
	s_add_i32 s14, s23, s58
	global_load_lds_dwordx4 v160, s[12:13] offset:128
	s_add_u32 s12, s12, 0x10080
	s_addc_u32 s13, s13, 0
	s_mov_b32 m0, s14
	s_nop 0
	global_load_lds_dwordx4 v156, s[12:13]
	s_add_i32 m0, s14, 0x2000
	s_nop 0
	global_load_lds_dwordx4 v160, s[12:13]
	s_add_i32 m0, s96, 0xffffff80
	s_nop 0
	global_load_lds_dwordx4 v154, s[26:27] offset:128
	s_add_i32 m0, s36, 0xffffff80
	s_nop 0
	global_load_lds_dwordx4 v158, s[26:27] offset:128
	s_waitcnt vmcnt(8)
	s_waitcnt lgkmcnt(0)
	s_barrier
	v_mfma_f32_16x16x32_bf16 v[68:71], v[16:19], v[188:191], v[68:71]
	v_mfma_f32_16x16x32_bf16 v[52:55], v[16:19], v[196:199], v[52:55]
	v_mfma_f32_16x16x32_bf16 v[36:39], v[16:19], v[204:207], v[36:39]
	v_mfma_f32_16x16x32_bf16 v[0:3], v[16:19], v[238:241], v[0:3]
	v_mfma_f32_16x16x32_bf16 v[68:71], v[20:23], v[192:195], v[68:71]
	v_mfma_f32_16x16x32_bf16 v[64:67], v[138:141], v[188:191], v[64:67]
	v_mfma_f32_16x16x32_bf16 v[52:55], v[20:23], v[200:203], v[52:55]
	v_mfma_f32_16x16x32_bf16 v[48:51], v[138:141], v[196:199], v[48:51]
	v_mfma_f32_16x16x32_bf16 v[36:39], v[20:23], v[234:237], v[36:39]
	v_mfma_f32_16x16x32_bf16 v[32:35], v[138:141], v[204:207], v[32:35]
	v_mfma_f32_16x16x32_bf16 v[20:23], v[20:23], v[242:245], v[0:3]
	v_mfma_f32_16x16x32_bf16 v[0:3], v[138:141], v[238:241], v[4:7]
	v_mfma_f32_16x16x32_bf16 v[64:67], v[142:145], v[192:195], v[64:67]
	v_mfma_f32_16x16x32_bf16 v[48:51], v[142:145], v[200:203], v[48:51]
	v_mfma_f32_16x16x32_bf16 v[32:35], v[142:145], v[234:237], v[32:35]
	v_mfma_f32_16x16x32_bf16 v[16:19], v[142:145], v[242:245], v[0:3]
	v_mfma_f32_16x16x32_bf16 v[0:3], v[146:149], v[188:191], v[60:63]
	v_mfma_f32_16x16x32_bf16 v[60:63], v[150:153], v[192:195], v[0:3]
	v_mfma_f32_16x16x32_bf16 v[0:3], v[180:183], v[188:191], v[56:59]
	v_mfma_f32_16x16x32_bf16 v[56:59], v[184:187], v[192:195], v[0:3]
	v_mfma_f32_16x16x32_bf16 v[0:3], v[146:149], v[196:199], v[44:47]
	v_mfma_f32_16x16x32_bf16 v[44:47], v[150:153], v[200:203], v[0:3]
	v_mfma_f32_16x16x32_bf16 v[0:3], v[180:183], v[196:199], v[40:43]
	v_mfma_f32_16x16x32_bf16 v[40:43], v[184:187], v[200:203], v[0:3]
	v_mfma_f32_16x16x32_bf16 v[0:3], v[146:149], v[204:207], v[28:31]
	v_mfma_f32_16x16x32_bf16 v[28:31], v[150:153], v[234:237], v[0:3]
	v_mfma_f32_16x16x32_bf16 v[0:3], v[180:183], v[204:207], v[24:27]
	v_mfma_f32_16x16x32_bf16 v[24:27], v[184:187], v[234:237], v[0:3]
	v_mfma_f32_16x16x32_bf16 v[0:3], v[146:149], v[238:241], v[12:15]
	v_mfma_f32_16x16x32_bf16 v[12:15], v[150:153], v[242:245], v[0:3]
	v_mfma_f32_16x16x32_bf16 v[0:3], v[180:183], v[238:241], v[8:11]
	v_mfma_f32_16x16x32_bf16 v[8:11], v[184:187], v[242:245], v[0:3]
	s_barrier
	s_add_i32 s22, s22, 2
	s_add_u32 s2, s2, 0x100
	s_addc_u32 s3, s3, 0
	s_add_u32 s20, s20, 0x100
	s_addc_u32 s21, s21, 0
	s_cmp_gt_u32 s22, 13
	s_cbranch_scc0 .LBB0_405
	s_and_b64 vcc, exec, s[42:43]
	s_cbranch_vccz .LBB0_418
	s_barrier
	s_andn2_b64 vcc, exec, s[38:39]
	s_mov_b64 s[2:3], -1
	s_cbranch_vccz .LBB0_419

.Lpl_in_j1:
	s_waitcnt lgkmcnt(0)
	s_barrier
	v_mfma_f32_16x16x32_bf16 v[134:137], v[0:3], v[190:193], 0
	v_mfma_f32_16x16x32_bf16 v[130:133], v[138:141], v[190:193], 0
	v_mfma_f32_16x16x32_bf16 v[118:121], v[0:3], v[198:201], 0
	v_mfma_f32_16x16x32_bf16 v[114:117], v[138:141], v[198:201], 0
	v_mfma_f32_16x16x32_bf16 v[102:105], v[0:3], v[222:225], 0
	v_mfma_f32_16x16x32_bf16 v[98:101], v[138:141], v[222:225], 0
	v_mfma_f32_16x16x32_bf16 v[84:87], v[0:3], v[230:233], 0
	v_mfma_f32_16x16x32_bf16 v[80:83], v[138:141], v[230:233], 0
	v_mfma_f32_16x16x32_bf16 v[134:137], v[4:7], v[194:197], v[134:137]
	v_mfma_f32_16x16x32_bf16 v[130:133], v[142:145], v[194:197], v[130:133]
	v_mfma_f32_16x16x32_bf16 v[118:121], v[4:7], v[202:205], v[118:121]
	v_mfma_f32_16x16x32_bf16 v[114:117], v[142:145], v[202:205], v[114:117]
	v_mfma_f32_16x16x32_bf16 v[102:105], v[4:7], v[226:229], v[102:105]
	v_mfma_f32_16x16x32_bf16 v[98:101], v[142:145], v[226:229], v[98:101]
	v_mfma_f32_16x16x32_bf16 v[84:87], v[4:7], v[234:237], v[84:87]
	v_mfma_f32_16x16x32_bf16 v[80:83], v[142:145], v[234:237], v[80:83]
	v_mfma_f32_16x16x32_bf16 v[126:129], v[146:149], v[190:193], 0
	v_mfma_f32_16x16x32_bf16 v[122:125], v[182:185], v[190:193], 0
	v_mfma_f32_16x16x32_bf16 v[110:113], v[146:149], v[198:201], 0
	v_mfma_f32_16x16x32_bf16 v[106:109], v[182:185], v[198:201], 0
	v_mfma_f32_16x16x32_bf16 v[92:95], v[146:149], v[222:225], 0
	v_mfma_f32_16x16x32_bf16 v[88:91], v[182:185], v[222:225], 0
	v_mfma_f32_16x16x32_bf16 v[76:79], v[146:149], v[230:233], 0
	v_mfma_f32_16x16x32_bf16 v[72:75], v[182:185], v[230:233], 0
	v_mfma_f32_16x16x32_bf16 v[126:129], v[150:153], v[194:197], v[126:129]
	v_mfma_f32_16x16x32_bf16 v[122:125], v[186:189], v[194:197], v[122:125]
	v_mfma_f32_16x16x32_bf16 v[110:113], v[150:153], v[202:205], v[110:113]
	v_mfma_f32_16x16x32_bf16 v[106:109], v[186:189], v[202:205], v[106:109]
	v_mfma_f32_16x16x32_bf16 v[92:95], v[150:153], v[226:229], v[92:95]
	v_mfma_f32_16x16x32_bf16 v[88:91], v[186:189], v[226:229], v[88:91]
	v_mfma_f32_16x16x32_bf16 v[76:79], v[150:153], v[234:237], v[76:79]
	v_mfma_f32_16x16x32_bf16 v[72:75], v[186:189], v[234:237], v[72:75]
	s_barrier
	s_add_i32 s33, s33, s78
	s_mov_b32 m0, s33
	ds_read_b128 v[190:193], v221 offset:16384
	ds_read_b128 v[194:197], v221 offset:17408
	ds_read_b128 v[198:201], v221 offset:18432
	ds_read_b128 v[202:205], v221 offset:19456
	ds_read_b128 v[222:225], v221 offset:20480
	ds_read_b128 v[226:229], v221 offset:21504
	ds_read_b128 v[230:233], v221 offset:22528
	ds_read_b128 v[234:237], v221 offset:23552
	global_load_lds_dwordx4 v156, s[12:13]
	s_add_i32 m0, s33, 0x2000
	s_add_u32 s42, s12, 0x10000
	s_addc_u32 s43, s13, 0
	s_add_i32 s33, s35, s78
	global_load_lds_dwordx4 v160, s[12:13]
	s_mov_b32 m0, s33
	s_nop 0
	global_load_lds_dwordx4 v156, s[42:43]
	s_add_i32 m0, s33, 0x2000
	s_nop 0
	global_load_lds_dwordx4 v160, s[42:43]
	s_mov_b64 s[42:43], s[14:15]
	s_mov_b32 m0, s79
	s_nop 0
	global_load_lds_dwordx4 v154, s[14:15]
	s_mov_b32 m0, s81
	s_nop 0
	global_load_lds_dwordx4 v158, s[14:15]
	s_cmp_lg_u32 s100, 0
	s_cbranch_scc1 .Lpl_in_r2
	s_waitcnt vmcnt(8)
	s_branch .Lpl_in_j2

.Lpl_in_j2:
	s_mov_b32 s100, 0
	s_waitcnt lgkmcnt(0)
	s_barrier
	v_mfma_f32_16x16x32_bf16 v[68:71], v[0:3], v[190:193], 0
	v_mfma_f32_16x16x32_bf16 v[64:67], v[138:141], v[190:193], 0
	v_mfma_f32_16x16x32_bf16 v[52:55], v[0:3], v[198:201], 0
	v_mfma_f32_16x16x32_bf16 v[48:51], v[138:141], v[198:201], 0
	v_mfma_f32_16x16x32_bf16 v[36:39], v[0:3], v[222:225], 0
	v_mfma_f32_16x16x32_bf16 v[32:35], v[138:141], v[222:225], 0
	v_mfma_f32_16x16x32_bf16 v[0:3], v[0:3], v[230:233], 0
	v_mfma_f32_16x16x32_bf16 v[68:71], v[4:7], v[194:197], v[68:71]
	v_mfma_f32_16x16x32_bf16 v[64:67], v[142:145], v[194:197], v[64:67]
	v_mfma_f32_16x16x32_bf16 v[52:55], v[4:7], v[202:205], v[52:55]
	v_mfma_f32_16x16x32_bf16 v[48:51], v[142:145], v[202:205], v[48:51]
	v_mfma_f32_16x16x32_bf16 v[36:39], v[4:7], v[226:229], v[36:39]
	v_mfma_f32_16x16x32_bf16 v[32:35], v[142:145], v[226:229], v[32:35]
	v_mfma_f32_16x16x32_bf16 v[0:3], v[4:7], v[234:237], v[0:3]
	v_mfma_f32_16x16x32_bf16 v[4:7], v[138:141], v[230:233], 0
	v_mfma_f32_16x16x32_bf16 v[4:7], v[142:145], v[234:237], v[4:7]
	v_mfma_f32_16x16x32_bf16 v[16:19], v[146:149], v[190:193], 0
	v_mfma_f32_16x16x32_bf16 v[60:63], v[150:153], v[194:197], v[16:19]
	v_mfma_f32_16x16x32_bf16 v[16:19], v[182:185], v[190:193], 0
	v_mfma_f32_16x16x32_bf16 v[56:59], v[186:189], v[194:197], v[16:19]
	v_mfma_f32_16x16x32_bf16 v[16:19], v[146:149], v[198:201], 0
	v_mfma_f32_16x16x32_bf16 v[44:47], v[150:153], v[202:205], v[16:19]
	v_mfma_f32_16x16x32_bf16 v[16:19], v[182:185], v[198:201], 0
	v_mfma_f32_16x16x32_bf16 v[40:43], v[186:189], v[202:205], v[16:19]
	v_mfma_f32_16x16x32_bf16 v[16:19], v[146:149], v[222:225], 0
	v_mfma_f32_16x16x32_bf16 v[28:31], v[150:153], v[226:229], v[16:19]
	v_mfma_f32_16x16x32_bf16 v[16:19], v[182:185], v[222:225], 0
	v_mfma_f32_16x16x32_bf16 v[12:15], v[146:149], v[230:233], 0
	v_mfma_f32_16x16x32_bf16 v[8:11], v[182:185], v[230:233], 0
	v_mfma_f32_16x16x32_bf16 v[24:27], v[186:189], v[226:229], v[16:19]
	v_mfma_f32_16x16x32_bf16 v[12:15], v[150:153], v[234:237], v[12:15]
	v_mfma_f32_16x16x32_bf16 v[8:11], v[186:189], v[234:237], v[8:11]
	s_barrier
	s_add_i32 s33, 0, 0x1c000
	ds_read_b128 v[16:19], v253 offset:32768
	ds_read_b128 v[20:23], v253 offset:33792
	ds_read_b128 v[138:141], v253 offset:34816
	ds_read_b128 v[142:145], v253 offset:35840
	ds_read_b128 v[146:149], v253 offset:49152
	ds_read_b128 v[150:153], v253 offset:50176
	ds_read_b128 v[182:185], v253 offset:51200
	ds_read_b128 v[186:189], v253 offset:52224
	s_add_u32 s14, s14, 0x40000
	s_addc_u32 s15, s15, 0
	s_mov_b32 m0, s92
	ds_read_b128 v[190:193], v221 offset:32768
	ds_read_b128 v[194:197], v221 offset:33792
	ds_read_b128 v[198:201], v221 offset:34816
	ds_read_b128 v[202:205], v221 offset:35840
	ds_read_b128 v[222:225], v221 offset:36864
	ds_read_b128 v[226:229], v221 offset:37888
	ds_read_b128 v[230:233], v221 offset:38912
	ds_read_b128 v[234:237], v221 offset:39936
	global_load_lds_dwordx4 v154, s[14:15]
	s_mov_b32 m0, s93
	s_nop 0
	global_load_lds_dwordx4 v158, s[14:15]
	s_waitcnt vmcnt(8)
	s_waitcnt lgkmcnt(0)
	s_barrier
	v_mfma_f32_16x16x32_bf16 v[134:137], v[16:19], v[190:193], v[134:137]
	v_mfma_f32_16x16x32_bf16 v[130:133], v[138:141], v[190:193], v[130:133]
	v_mfma_f32_16x16x32_bf16 v[118:121], v[16:19], v[198:201], v[118:121]
	v_mfma_f32_16x16x32_bf16 v[114:117], v[138:141], v[198:201], v[114:117]
	v_mfma_f32_16x16x32_bf16 v[102:105], v[16:19], v[222:225], v[102:105]
	v_mfma_f32_16x16x32_bf16 v[98:101], v[138:141], v[222:225], v[98:101]
	v_mfma_f32_16x16x32_bf16 v[84:87], v[16:19], v[230:233], v[84:87]
	v_mfma_f32_16x16x32_bf16 v[80:83], v[138:141], v[230:233], v[80:83]
	v_mfma_f32_16x16x32_bf16 v[134:137], v[20:23], v[194:197], v[134:137]
	v_mfma_f32_16x16x32_bf16 v[130:133], v[142:145], v[194:197], v[130:133]
	v_mfma_f32_16x16x32_bf16 v[118:121], v[20:23], v[202:205], v[118:121]
	v_mfma_f32_16x16x32_bf16 v[114:117], v[142:145], v[202:205], v[114:117]
	v_mfma_f32_16x16x32_bf16 v[102:105], v[20:23], v[226:229], v[102:105]
	v_mfma_f32_16x16x32_bf16 v[98:101], v[142:145], v[226:229], v[98:101]
	v_mfma_f32_16x16x32_bf16 v[84:87], v[20:23], v[234:237], v[84:87]
	v_mfma_f32_16x16x32_bf16 v[80:83], v[142:145], v[234:237], v[80:83]
	v_mfma_f32_16x16x32_bf16 v[126:129], v[146:149], v[190:193], v[126:129]
	v_mfma_f32_16x16x32_bf16 v[122:125], v[182:185], v[190:193], v[122:125]
	v_mfma_f32_16x16x32_bf16 v[110:113], v[146:149], v[198:201], v[110:113]
	v_mfma_f32_16x16x32_bf16 v[106:109], v[182:185], v[198:201], v[106:109]
	v_mfma_f32_16x16x32_bf16 v[92:95], v[146:149], v[222:225], v[92:95]
	v_mfma_f32_16x16x32_bf16 v[88:91], v[182:185], v[222:225], v[88:91]
	v_mfma_f32_16x16x32_bf16 v[76:79], v[146:149], v[230:233], v[76:79]
	v_mfma_f32_16x16x32_bf16 v[72:75], v[182:185], v[230:233], v[72:75]
	v_mfma_f32_16x16x32_bf16 v[126:129], v[150:153], v[194:197], v[126:129]
	v_mfma_f32_16x16x32_bf16 v[122:125], v[186:189], v[194:197], v[122:125]
	v_mfma_f32_16x16x32_bf16 v[110:113], v[150:153], v[202:205], v[110:113]
	v_mfma_f32_16x16x32_bf16 v[106:109], v[186:189], v[202:205], v[106:109]
	v_mfma_f32_16x16x32_bf16 v[92:95], v[150:153], v[226:229], v[92:95]
	v_mfma_f32_16x16x32_bf16 v[88:91], v[186:189], v[226:229], v[88:91]
	v_mfma_f32_16x16x32_bf16 v[76:79], v[150:153], v[234:237], v[76:79]
	v_mfma_f32_16x16x32_bf16 v[72:75], v[186:189], v[234:237], v[72:75]
	s_barrier
	s_add_i32 s14, s67, s78
	s_add_i32 m0, s14, 0xffffff80
	ds_read_b128 v[190:193], v221 offset:49152
	ds_read_b128 v[194:197], v221 offset:50176
	ds_read_b128 v[198:201], v221 offset:51200
	ds_read_b128 v[202:205], v221 offset:52224
	ds_read_b128 v[222:225], v221 offset:53248
	ds_read_b128 v[226:229], v221 offset:54272
	ds_read_b128 v[230:233], v221 offset:55296
	ds_read_b128 v[234:237], v221 offset:56320
	global_load_lds_dwordx4 v156, s[12:13] offset:128
	s_add_i32 m0, s14, 0x1f80
	s_add_i32 s14, s33, s78
	global_load_lds_dwordx4 v160, s[12:13] offset:128
	s_add_u32 s12, s12, 0x10080
	s_addc_u32 s13, s13, 0
	s_mov_b32 m0, s14
	s_nop 0
	global_load_lds_dwordx4 v156, s[12:13]
	s_add_i32 m0, s14, 0x2000
	s_nop 0
	global_load_lds_dwordx4 v160, s[12:13]
	s_add_i32 m0, s21, 0xffffff80
	s_nop 0
	global_load_lds_dwordx4 v154, s[42:43] offset:128
	s_add_i32 m0, s61, 0xffffff80
	s_nop 0
	global_load_lds_dwordx4 v158, s[42:43] offset:128
	s_waitcnt vmcnt(8)
	s_waitcnt lgkmcnt(0)
	s_barrier
	v_mfma_f32_16x16x32_bf16 v[68:71], v[16:19], v[190:193], v[68:71]
	v_mfma_f32_16x16x32_bf16 v[52:55], v[16:19], v[198:201], v[52:55]
	v_mfma_f32_16x16x32_bf16 v[36:39], v[16:19], v[222:225], v[36:39]
	v_mfma_f32_16x16x32_bf16 v[0:3], v[16:19], v[230:233], v[0:3]
	v_mfma_f32_16x16x32_bf16 v[68:71], v[20:23], v[194:197], v[68:71]
	v_mfma_f32_16x16x32_bf16 v[64:67], v[138:141], v[190:193], v[64:67]
	v_mfma_f32_16x16x32_bf16 v[52:55], v[20:23], v[202:205], v[52:55]
	v_mfma_f32_16x16x32_bf16 v[48:51], v[138:141], v[198:201], v[48:51]
	v_mfma_f32_16x16x32_bf16 v[36:39], v[20:23], v[226:229], v[36:39]
	v_mfma_f32_16x16x32_bf16 v[32:35], v[138:141], v[222:225], v[32:35]
	v_mfma_f32_16x16x32_bf16 v[20:23], v[20:23], v[234:237], v[0:3]
	v_mfma_f32_16x16x32_bf16 v[0:3], v[138:141], v[230:233], v[4:7]
	v_mfma_f32_16x16x32_bf16 v[64:67], v[142:145], v[194:197], v[64:67]
	v_mfma_f32_16x16x32_bf16 v[48:51], v[142:145], v[202:205], v[48:51]
	v_mfma_f32_16x16x32_bf16 v[32:35], v[142:145], v[226:229], v[32:35]
	v_mfma_f32_16x16x32_bf16 v[16:19], v[142:145], v[234:237], v[0:3]
	v_mfma_f32_16x16x32_bf16 v[0:3], v[146:149], v[190:193], v[60:63]
	v_mfma_f32_16x16x32_bf16 v[60:63], v[150:153], v[194:197], v[0:3]
	v_mfma_f32_16x16x32_bf16 v[0:3], v[182:185], v[190:193], v[56:59]
	v_mfma_f32_16x16x32_bf16 v[56:59], v[186:189], v[194:197], v[0:3]
	v_mfma_f32_16x16x32_bf16 v[0:3], v[146:149], v[198:201], v[44:47]
	v_mfma_f32_16x16x32_bf16 v[44:47], v[150:153], v[202:205], v[0:3]
	v_mfma_f32_16x16x32_bf16 v[0:3], v[182:185], v[198:201], v[40:43]
	v_mfma_f32_16x16x32_bf16 v[40:43], v[186:189], v[202:205], v[0:3]
	v_mfma_f32_16x16x32_bf16 v[0:3], v[146:149], v[222:225], v[28:31]
	v_mfma_f32_16x16x32_bf16 v[28:31], v[150:153], v[226:229], v[0:3]
	v_mfma_f32_16x16x32_bf16 v[0:3], v[182:185], v[222:225], v[24:27]
	v_mfma_f32_16x16x32_bf16 v[24:27], v[186:189], v[226:229], v[0:3]
	v_mfma_f32_16x16x32_bf16 v[0:3], v[146:149], v[230:233], v[12:15]
	v_mfma_f32_16x16x32_bf16 v[12:15], v[150:153], v[234:237], v[0:3]
	v_mfma_f32_16x16x32_bf16 v[0:3], v[182:185], v[230:233], v[8:11]
	v_mfma_f32_16x16x32_bf16 v[8:11], v[186:189], v[234:237], v[0:3]
	s_barrier
	s_add_i32 s27, s27, 2
	s_add_u32 s4, s4, 0x100
	s_addc_u32 s5, s5, 0
	s_add_u32 s19, s19, 0x100
	s_addc_u32 s26, s26, 0
	.p2align 6
.LBB0_750:
	s_add_u32 s12, s4, 0xfffc0080
	s_addc_u32 s13, s5, -1
	s_add_i32 s33, 0, 0x10000
	s_cmp_eq_u32 s27, 12
	s_cselect_b32 s15, s3, s13
	s_cselect_b32 s14, s16, s12
	s_cselect_b32 s13, s17, s26
	s_cselect_b32 s12, s18, s19
	s_add_i32 s35, 0, 0x14000
	ds_read_b128 v[0:3], v253
	ds_read_b128 v[4:7], v253 offset:1024
	ds_read_b128 v[138:141], v253 offset:2048
	ds_read_b128 v[142:145], v253 offset:3072
	ds_read_b128 v[146:149], v253 offset:16384
	ds_read_b128 v[150:153], v253 offset:17408
	ds_read_b128 v[182:185], v253 offset:18432
	ds_read_b128 v[186:189], v253 offset:19456
	s_add_i32 m0, s79, 0xc000
	ds_read_b128 v[190:193], v221
	ds_read_b128 v[194:197], v221 offset:1024
	ds_read_b128 v[198:201], v221 offset:2048
	ds_read_b128 v[202:205], v221 offset:3072
	ds_read_b128 v[222:225], v221 offset:4096
	ds_read_b128 v[226:229], v221 offset:5120
	ds_read_b128 v[230:233], v221 offset:6144
	ds_read_b128 v[234:237], v221 offset:7168
	global_load_lds_dwordx4 v168, s[4:5]
	s_add_i32 m0, s79, 0xe000
	s_nop 0
	global_load_lds_dwordx4 v170, s[4:5]
	s_waitcnt vmcnt(8)
	s_waitcnt lgkmcnt(0)
	s_barrier
	v_mfma_f32_16x16x32_bf16 v[134:137], v[0:3], v[190:193], v[134:137]
	v_mfma_f32_16x16x32_bf16 v[130:133], v[138:141], v[190:193], v[130:133]
	v_mfma_f32_16x16x32_bf16 v[118:121], v[0:3], v[198:201], v[118:121]
	v_mfma_f32_16x16x32_bf16 v[114:117], v[138:141], v[198:201], v[114:117]
	v_mfma_f32_16x16x32_bf16 v[102:105], v[0:3], v[222:225], v[102:105]
	v_mfma_f32_16x16x32_bf16 v[98:101], v[138:141], v[222:225], v[98:101]
	v_mfma_f32_16x16x32_bf16 v[84:87], v[0:3], v[230:233], v[84:87]
	v_mfma_f32_16x16x32_bf16 v[80:83], v[138:141], v[230:233], v[80:83]
	v_mfma_f32_16x16x32_bf16 v[134:137], v[4:7], v[194:197], v[134:137]
	v_mfma_f32_16x16x32_bf16 v[130:133], v[142:145], v[194:197], v[130:133]
	v_mfma_f32_16x16x32_bf16 v[118:121], v[4:7], v[202:205], v[118:121]
	v_mfma_f32_16x16x32_bf16 v[114:117], v[142:145], v[202:205], v[114:117]
	v_mfma_f32_16x16x32_bf16 v[102:105], v[4:7], v[226:229], v[102:105]
	v_mfma_f32_16x16x32_bf16 v[98:101], v[142:145], v[226:229], v[98:101]
	v_mfma_f32_16x16x32_bf16 v[84:87], v[4:7], v[234:237], v[84:87]
	v_mfma_f32_16x16x32_bf16 v[80:83], v[142:145], v[234:237], v[80:83]
	v_mfma_f32_16x16x32_bf16 v[126:129], v[146:149], v[190:193], v[126:129]
	v_mfma_f32_16x16x32_bf16 v[122:125], v[182:185], v[190:193], v[122:125]
	v_mfma_f32_16x16x32_bf16 v[110:113], v[146:149], v[198:201], v[110:113]
	v_mfma_f32_16x16x32_bf16 v[106:109], v[182:185], v[198:201], v[106:109]
	v_mfma_f32_16x16x32_bf16 v[92:95], v[146:149], v[222:225], v[92:95]
	v_mfma_f32_16x16x32_bf16 v[88:91], v[182:185], v[222:225], v[88:91]
	v_mfma_f32_16x16x32_bf16 v[76:79], v[146:149], v[230:233], v[76:79]
	v_mfma_f32_16x16x32_bf16 v[72:75], v[182:185], v[230:233], v[72:75]
	v_mfma_f32_16x16x32_bf16 v[126:129], v[150:153], v[194:197], v[126:129]
	v_mfma_f32_16x16x32_bf16 v[122:125], v[186:189], v[194:197], v[122:125]
	v_mfma_f32_16x16x32_bf16 v[110:113], v[150:153], v[202:205], v[110:113]
	v_mfma_f32_16x16x32_bf16 v[106:109], v[186:189], v[202:205], v[106:109]
	v_mfma_f32_16x16x32_bf16 v[92:95], v[150:153], v[226:229], v[92:95]
	v_mfma_f32_16x16x32_bf16 v[88:91], v[186:189], v[226:229], v[88:91]
	v_mfma_f32_16x16x32_bf16 v[76:79], v[150:153], v[234:237], v[76:79]
	v_mfma_f32_16x16x32_bf16 v[72:75], v[186:189], v[234:237], v[72:75]
	s_barrier
	s_add_i32 s33, s33, s78
	s_mov_b32 m0, s33
	ds_read_b128 v[190:193], v221 offset:16384
	ds_read_b128 v[194:197], v221 offset:17408
	ds_read_b128 v[198:201], v221 offset:18432
	ds_read_b128 v[202:205], v221 offset:19456
	ds_read_b128 v[222:225], v221 offset:20480
	ds_read_b128 v[226:229], v221 offset:21504
	ds_read_b128 v[230:233], v221 offset:22528
	ds_read_b128 v[234:237], v221 offset:23552
	global_load_lds_dwordx4 v156, s[12:13]
	s_add_i32 m0, s33, 0x2000
	s_add_u32 s42, s12, 0x10000
	s_addc_u32 s43, s13, 0
	s_add_i32 s33, s35, s78
	global_load_lds_dwordx4 v160, s[12:13]
	s_mov_b32 m0, s33
	s_nop 0
	global_load_lds_dwordx4 v156, s[42:43]
	s_add_i32 m0, s33, 0x2000
	s_nop 0
	global_load_lds_dwordx4 v160, s[42:43]
	s_mov_b64 s[42:43], s[14:15]
	s_mov_b32 m0, s79
	s_nop 0
	global_load_lds_dwordx4 v154, s[14:15]
	s_mov_b32 m0, s81
	s_nop 0
	global_load_lds_dwordx4 v158, s[14:15]
	s_waitcnt vmcnt(8)
	s_waitcnt lgkmcnt(0)
	s_barrier
	v_mfma_f32_16x16x32_bf16 v[68:71], v[0:3], v[190:193], v[68:71]
	v_mfma_f32_16x16x32_bf16 v[64:67], v[138:141], v[190:193], v[64:67]
	v_mfma_f32_16x16x32_bf16 v[52:55], v[0:3], v[198:201], v[52:55]
	v_mfma_f32_16x16x32_bf16 v[48:51], v[138:141], v[198:201], v[48:51]
	v_mfma_f32_16x16x32_bf16 v[36:39], v[0:3], v[222:225], v[36:39]
	v_mfma_f32_16x16x32_bf16 v[32:35], v[138:141], v[222:225], v[32:35]
	v_mfma_f32_16x16x32_bf16 v[0:3], v[0:3], v[230:233], v[20:23]
	v_mfma_f32_16x16x32_bf16 v[68:71], v[4:7], v[194:197], v[68:71]
	v_mfma_f32_16x16x32_bf16 v[64:67], v[142:145], v[194:197], v[64:67]
	v_mfma_f32_16x16x32_bf16 v[52:55], v[4:7], v[202:205], v[52:55]
	v_mfma_f32_16x16x32_bf16 v[48:51], v[142:145], v[202:205], v[48:51]
	v_mfma_f32_16x16x32_bf16 v[36:39], v[4:7], v[226:229], v[36:39]
	v_mfma_f32_16x16x32_bf16 v[32:35], v[142:145], v[226:229], v[32:35]
	v_mfma_f32_16x16x32_bf16 v[0:3], v[4:7], v[234:237], v[0:3]
	v_mfma_f32_16x16x32_bf16 v[4:7], v[138:141], v[230:233], v[16:19]
	v_mfma_f32_16x16x32_bf16 v[4:7], v[142:145], v[234:237], v[4:7]
	v_mfma_f32_16x16x32_bf16 v[16:19], v[146:149], v[190:193], v[60:63]
	v_mfma_f32_16x16x32_bf16 v[60:63], v[150:153], v[194:197], v[16:19]
	v_mfma_f32_16x16x32_bf16 v[16:19], v[182:185], v[190:193], v[56:59]
	v_mfma_f32_16x16x32_bf16 v[56:59], v[186:189], v[194:197], v[16:19]
	v_mfma_f32_16x16x32_bf16 v[16:19], v[146:149], v[198:201], v[44:47]
	v_mfma_f32_16x16x32_bf16 v[44:47], v[150:153], v[202:205], v[16:19]
	v_mfma_f32_16x16x32_bf16 v[16:19], v[182:185], v[198:201], v[40:43]
	v_mfma_f32_16x16x32_bf16 v[40:43], v[186:189], v[202:205], v[16:19]
	v_mfma_f32_16x16x32_bf16 v[16:19], v[146:149], v[222:225], v[28:31]
	v_mfma_f32_16x16x32_bf16 v[28:31], v[150:153], v[226:229], v[16:19]
	v_mfma_f32_16x16x32_bf16 v[16:19], v[182:185], v[222:225], v[24:27]
	v_mfma_f32_16x16x32_bf16 v[12:15], v[146:149], v[230:233], v[12:15]
	v_mfma_f32_16x16x32_bf16 v[8:11], v[182:185], v[230:233], v[8:11]
	v_mfma_f32_16x16x32_bf16 v[24:27], v[186:189], v[226:229], v[16:19]
	v_mfma_f32_16x16x32_bf16 v[12:15], v[150:153], v[234:237], v[12:15]
	v_mfma_f32_16x16x32_bf16 v[8:11], v[186:189], v[234:237], v[8:11]
	s_barrier
	s_add_i32 s33, 0, 0x1c000
	ds_read_b128 v[16:19], v253 offset:32768
	ds_read_b128 v[20:23], v253 offset:33792
	ds_read_b128 v[138:141], v253 offset:34816
	ds_read_b128 v[142:145], v253 offset:35840
	ds_read_b128 v[146:149], v253 offset:49152
	ds_read_b128 v[150:153], v253 offset:50176
	ds_read_b128 v[182:185], v253 offset:51200
	ds_read_b128 v[186:189], v253 offset:52224
	s_add_u32 s14, s14, 0x40000
	s_addc_u32 s15, s15, 0
	s_mov_b32 m0, s92
	ds_read_b128 v[190:193], v221 offset:32768
	ds_read_b128 v[194:197], v221 offset:33792
	ds_read_b128 v[198:201], v221 offset:34816
	ds_read_b128 v[202:205], v221 offset:35840
	ds_read_b128 v[222:225], v221 offset:36864
	ds_read_b128 v[226:229], v221 offset:37888
	ds_read_b128 v[230:233], v221 offset:38912
	ds_read_b128 v[234:237], v221 offset:39936
	global_load_lds_dwordx4 v154, s[14:15]
	s_mov_b32 m0, s93
	s_nop 0
	global_load_lds_dwordx4 v158, s[14:15]
	s_waitcnt vmcnt(8)
	s_waitcnt lgkmcnt(0)
	s_barrier
	v_mfma_f32_16x16x32_bf16 v[134:137], v[16:19], v[190:193], v[134:137]
	v_mfma_f32_16x16x32_bf16 v[130:133], v[138:141], v[190:193], v[130:133]
	v_mfma_f32_16x16x32_bf16 v[118:121], v[16:19], v[198:201], v[118:121]
	v_mfma_f32_16x16x32_bf16 v[114:117], v[138:141], v[198:201], v[114:117]
	v_mfma_f32_16x16x32_bf16 v[102:105], v[16:19], v[222:225], v[102:105]
	v_mfma_f32_16x16x32_bf16 v[98:101], v[138:141], v[222:225], v[98:101]
	v_mfma_f32_16x16x32_bf16 v[84:87], v[16:19], v[230:233], v[84:87]
	v_mfma_f32_16x16x32_bf16 v[80:83], v[138:141], v[230:233], v[80:83]
	v_mfma_f32_16x16x32_bf16 v[134:137], v[20:23], v[194:197], v[134:137]
	v_mfma_f32_16x16x32_bf16 v[130:133], v[142:145], v[194:197], v[130:133]
	v_mfma_f32_16x16x32_bf16 v[118:121], v[20:23], v[202:205], v[118:121]
	v_mfma_f32_16x16x32_bf16 v[114:117], v[142:145], v[202:205], v[114:117]
	v_mfma_f32_16x16x32_bf16 v[102:105], v[20:23], v[226:229], v[102:105]
	v_mfma_f32_16x16x32_bf16 v[98:101], v[142:145], v[226:229], v[98:101]
	v_mfma_f32_16x16x32_bf16 v[84:87], v[20:23], v[234:237], v[84:87]
	v_mfma_f32_16x16x32_bf16 v[80:83], v[142:145], v[234:237], v[80:83]
	v_mfma_f32_16x16x32_bf16 v[126:129], v[146:149], v[190:193], v[126:129]
	v_mfma_f32_16x16x32_bf16 v[122:125], v[182:185], v[190:193], v[122:125]
	v_mfma_f32_16x16x32_bf16 v[110:113], v[146:149], v[198:201], v[110:113]
	v_mfma_f32_16x16x32_bf16 v[106:109], v[182:185], v[198:201], v[106:109]
	v_mfma_f32_16x16x32_bf16 v[92:95], v[146:149], v[222:225], v[92:95]
	v_mfma_f32_16x16x32_bf16 v[88:91], v[182:185], v[222:225], v[88:91]
	v_mfma_f32_16x16x32_bf16 v[76:79], v[146:149], v[230:233], v[76:79]
	v_mfma_f32_16x16x32_bf16 v[72:75], v[182:185], v[230:233], v[72:75]
	v_mfma_f32_16x16x32_bf16 v[126:129], v[150:153], v[194:197], v[126:129]
	v_mfma_f32_16x16x32_bf16 v[122:125], v[186:189], v[194:197], v[122:125]
	v_mfma_f32_16x16x32_bf16 v[110:113], v[150:153], v[202:205], v[110:113]
	v_mfma_f32_16x16x32_bf16 v[106:109], v[186:189], v[202:205], v[106:109]
	v_mfma_f32_16x16x32_bf16 v[92:95], v[150:153], v[226:229], v[92:95]
	v_mfma_f32_16x16x32_bf16 v[88:91], v[186:189], v[226:229], v[88:91]
	v_mfma_f32_16x16x32_bf16 v[76:79], v[150:153], v[234:237], v[76:79]
	v_mfma_f32_16x16x32_bf16 v[72:75], v[186:189], v[234:237], v[72:75]
	s_barrier
	s_add_i32 s14, s67, s78
	s_add_i32 m0, s14, 0xffffff80
	ds_read_b128 v[190:193], v221 offset:49152
	ds_read_b128 v[194:197], v221 offset:50176
	ds_read_b128 v[198:201], v221 offset:51200
	ds_read_b128 v[202:205], v221 offset:52224
	ds_read_b128 v[222:225], v221 offset:53248
	ds_read_b128 v[226:229], v221 offset:54272
	ds_read_b128 v[230:233], v221 offset:55296
	ds_read_b128 v[234:237], v221 offset:56320
	global_load_lds_dwordx4 v156, s[12:13] offset:128
	s_add_i32 m0, s14, 0x1f80
	s_add_i32 s14, s33, s78
	global_load_lds_dwordx4 v160, s[12:13] offset:128
	s_add_u32 s12, s12, 0x10080
	s_addc_u32 s13, s13, 0
	s_mov_b32 m0, s14
	s_nop 0
	global_load_lds_dwordx4 v156, s[12:13]
	s_add_i32 m0, s14, 0x2000
	s_nop 0
	global_load_lds_dwordx4 v160, s[12:13]
	s_add_i32 m0, s21, 0xffffff80
	s_nop 0
	global_load_lds_dwordx4 v154, s[42:43] offset:128
	s_add_i32 m0, s61, 0xffffff80
	s_nop 0
	global_load_lds_dwordx4 v158, s[42:43] offset:128
	s_waitcnt vmcnt(8)
	s_waitcnt lgkmcnt(0)
	s_barrier
	v_mfma_f32_16x16x32_bf16 v[68:71], v[16:19], v[190:193], v[68:71]
	v_mfma_f32_16x16x32_bf16 v[52:55], v[16:19], v[198:201], v[52:55]
	v_mfma_f32_16x16x32_bf16 v[36:39], v[16:19], v[222:225], v[36:39]
	v_mfma_f32_16x16x32_bf16 v[0:3], v[16:19], v[230:233], v[0:3]
	v_mfma_f32_16x16x32_bf16 v[68:71], v[20:23], v[194:197], v[68:71]
	v_mfma_f32_16x16x32_bf16 v[64:67], v[138:141], v[190:193], v[64:67]
	v_mfma_f32_16x16x32_bf16 v[52:55], v[20:23], v[202:205], v[52:55]
	v_mfma_f32_16x16x32_bf16 v[48:51], v[138:141], v[198:201], v[48:51]
	v_mfma_f32_16x16x32_bf16 v[36:39], v[20:23], v[226:229], v[36:39]
	v_mfma_f32_16x16x32_bf16 v[32:35], v[138:141], v[222:225], v[32:35]
	v_mfma_f32_16x16x32_bf16 v[20:23], v[20:23], v[234:237], v[0:3]
	v_mfma_f32_16x16x32_bf16 v[0:3], v[138:141], v[230:233], v[4:7]
	v_mfma_f32_16x16x32_bf16 v[64:67], v[142:145], v[194:197], v[64:67]
	v_mfma_f32_16x16x32_bf16 v[48:51], v[142:145], v[202:205], v[48:51]
	v_mfma_f32_16x16x32_bf16 v[32:35], v[142:145], v[226:229], v[32:35]
	v_mfma_f32_16x16x32_bf16 v[16:19], v[142:145], v[234:237], v[0:3]
	v_mfma_f32_16x16x32_bf16 v[0:3], v[146:149], v[190:193], v[60:63]
	v_mfma_f32_16x16x32_bf16 v[60:63], v[150:153], v[194:197], v[0:3]
	v_mfma_f32_16x16x32_bf16 v[0:3], v[182:185], v[190:193], v[56:59]
	v_mfma_f32_16x16x32_bf16 v[56:59], v[186:189], v[194:197], v[0:3]
	v_mfma_f32_16x16x32_bf16 v[0:3], v[146:149], v[198:201], v[44:47]
	v_mfma_f32_16x16x32_bf16 v[44:47], v[150:153], v[202:205], v[0:3]
	v_mfma_f32_16x16x32_bf16 v[0:3], v[182:185], v[198:201], v[40:43]
	v_mfma_f32_16x16x32_bf16 v[40:43], v[186:189], v[202:205], v[0:3]
	v_mfma_f32_16x16x32_bf16 v[0:3], v[146:149], v[222:225], v[28:31]
	v_mfma_f32_16x16x32_bf16 v[28:31], v[150:153], v[226:229], v[0:3]
	v_mfma_f32_16x16x32_bf16 v[0:3], v[182:185], v[222:225], v[24:27]
	v_mfma_f32_16x16x32_bf16 v[24:27], v[186:189], v[226:229], v[0:3]
	v_mfma_f32_16x16x32_bf16 v[0:3], v[146:149], v[230:233], v[12:15]
	v_mfma_f32_16x16x32_bf16 v[12:15], v[150:153], v[234:237], v[0:3]
	v_mfma_f32_16x16x32_bf16 v[0:3], v[182:185], v[230:233], v[8:11]
	v_mfma_f32_16x16x32_bf16 v[8:11], v[186:189], v[234:237], v[0:3]
	s_barrier
	s_add_i32 s27, s27, 2
	s_add_u32 s4, s4, 0x100
	s_addc_u32 s5, s5, 0
	s_add_u32 s19, s19, 0x100
	s_addc_u32 s26, s26, 0
	s_cmp_gt_u32 s27, 13
	s_cbranch_scc0 .LBB0_750
	v_readlane_b32 s4, v252, 30
	v_readlane_b32 s5, v252, 31
	s_and_b64 vcc, exec, s[4:5]
	s_cbranch_vccz .LBB0_753
	s_barrier
